# p1wait + DD_B 12->11: P1 streaming CUs take one page fewer (E=256), GEMM CUs become the P1 critical path
# baseline (speedup 1.0000x reference)
.LBB0_229:
	s_or_b64 exec, exec, s[0:1]
	s_cmpk_gt_i32 s85, 0xef
	s_barrier
	s_cbranch_scc0 .LBB0_231
	s_mul_i32 s0, s85, 11
	s_add_i32 s6, s0, -2560
	s_mov_b64 s[0:1], 0
	s_branch .LBB0_232

.LBB0_232:
	s_andn2_b64 vcc, exec, s[0:1]
	s_mov_b32 s33, 11
	v_writelane_b32 v245, s85, 50
	s_cbranch_vccnz .LBB0_234
	s_mov_b32 s33, 10
	s_mul_i32 s6, s30, 10

.LBB0_624:
	v_readlane_b32 s4, v245, 2
	v_readlane_b32 s7, v245, 5
	s_bitcmp0_b32 s7, 5
	v_readlane_b32 s5, v245, 3
	v_readlane_b32 s6, v245, 4
	s_cbranch_scc1 .LBB0_635
	s_and_b32 s33, s95, -2
	s_ashr_i32 s1, s95, 31
	s_add_i32 s0, s33, s1
	s_xor_b32 s2, s0, s1
	v_cvt_f32_u32_e32 v1, s2
	v_readlane_b32 s0, v245, 54
	s_lshl_b32 s0, s0, 1
	s_sub_i32 s3, s33, s0
	v_rcp_iflag_f32_e32 v1, v1
	s_addk_i32 s3, 0x6ff
	s_ashr_i32 s4, s3, 31
	s_sub_i32 s5, 0, s2
	v_mul_f32_e32 v1, 0x4f7ffffe, v1
	v_cvt_u32_f32_e32 v1, v1
	s_xor_b32 s56, s4, s1
	s_abs_i32 s3, s3
	v_mov_b32_e32 v131, v0
	v_readfirstlane_b32 s1, v1
	s_mul_i32 s5, s5, s1
	s_mul_hi_u32 s4, s1, s5
	s_add_i32 s1, s1, s4
	s_mul_hi_u32 s1, s3, s1
	s_mul_i32 s4, s1, s2
	s_sub_i32 s3, s3, s4
	s_add_i32 s5, s1, 1
	s_sub_i32 s4, s3, s2
	s_cmp_ge_u32 s3, s2
	s_cselect_b32 s1, s5, s1
	s_cselect_b32 s3, s4, s3
	s_add_i32 s4, s1, 1
	s_cmp_ge_u32 s3, s2
	s_cselect_b32 s1, s4, s1
	s_xor_b32 s57, s1, s56
	s_sub_i32 s68, s57, s56
	s_cmp_lt_i32 s68, 1
	v_readfirstlane_b32 s1, v131
	s_cbranch_scc1 .LBB0_635
	s_add_u32 s2, s96, 0xce00000
	s_addc_u32 s3, s97, 0
	s_ashr_i32 s58, s1, 6
	s_ashr_i32 s1, s0, 31
	v_readlane_b32 s8, v245, 9
	s_add_i32 s6, s0, 0x100
	s_lshl_b64 s[0:1], s[0:1], 2
	v_readlane_b32 s10, v245, 11
	v_readlane_b32 s11, v245, 12
	s_add_u32 s0, s10, s0
	s_addc_u32 s1, s11, s1
	v_mov_b32_e32 v187, 0
	global_load_dword v1, v187, s[0:1] offset:1024
	s_cmp_lg_u32 s68, 1
	s_cselect_b32 s4, s33, 0
	s_ashr_i32 s5, s4, 31
	s_lshl_b64 s[4:5], s[4:5], 2
	s_add_u32 s0, s0, s4
	v_readlane_b32 s16, v245, 17
	v_readlane_b32 s20, v245, 21
	s_addc_u32 s1, s1, s5
	s_lshl_b32 s4, s58, 4
	v_readlane_b32 s9, v245, 10
	v_readlane_b32 s17, v245, 18
	v_readlane_b32 s21, v245, 22
	s_ashr_i32 s8, s6, 4
	global_load_dword v133, v187, s[0:1] offset:1024
	s_or_b32 s16, s4, 1
	s_or_b32 s20, s4, 2
	s_or_b32 s24, s4, 3
	s_or_b32 s30, s4, 4
	s_or_b32 s36, s4, 5
	s_or_b32 s60, s4, 6
	s_or_b32 s0, s4, 7
	s_ashr_i32 s5, s4, 31
	s_ashr_i32 s9, s8, 31
	s_ashr_i32 s17, s16, 31
	s_ashr_i32 s21, s20, 31
	s_ashr_i32 s25, s24, 31
	s_ashr_i32 s31, s30, 31
	s_ashr_i32 s37, s36, 31
	s_ashr_i32 s61, s60, 31
	s_ashr_i32 s1, s0, 31
	s_lshl_b64 s[6:7], s[4:5], 9
	s_lshl_b64 s[8:9], s[8:9], 10
	s_lshl_b64 s[38:39], s[16:17], 9
	s_lshl_b64 s[40:41], s[20:21], 9
	s_lshl_b64 s[42:43], s[24:25], 9
	s_lshl_b64 s[44:45], s[30:31], 9
	s_lshl_b64 s[46:47], s[36:37], 9
	s_lshl_b64 s[48:49], s[60:61], 9
	s_lshl_b64 s[50:51], s[0:1], 9
	v_and_b32_e32 v130, 63, v131
	s_add_u32 s8, s2, s8
	v_lshlrev_b32_e32 v186, 3, v130
	s_addc_u32 s9, s3, s9
	s_waitcnt vmcnt(0)
	v_lshl_add_u64 v[34:35], s[8:9], 0, v[186:187]
	v_readlane_b32 s12, v245, 13
	v_readlane_b32 s13, v245, 14
	v_lshlrev_b32_e32 v132, 4, v130
	v_readlane_b32 s14, v245, 15
	v_readlane_b32 s15, v245, 16
	v_readlane_b32 s18, v245, 19
	v_readlane_b32 s19, v245, 20
	v_readlane_b32 s22, v245, 23
	v_readlane_b32 s23, v245, 24
	s_mov_b32 s94, s85
	s_mov_b32 s69, 0x1000000
	v_add_co_u32_e32 v36, vcc, s69, v34
	v_bfe_u32 v134, v131, 2, 4
	s_nop 0
	v_addc_co_u32_e32 v37, vcc, 0, v35, vcc
	v_ashrrev_i32_e32 v137, 6, v131
	v_bfe_u32 v139, v131, 5, 1
	v_ashrrev_i32_e32 v138, 7, v131
	v_lshlrev_b32_e32 v135, 1, v139
	v_and_b32_e32 v136, 31, v131
	v_lshl_add_u64 v[188:189], s[2:3], 0, v[186:187]
	v_lshlrev_b32_e32 v186, 4, v136
	s_mov_b64 s[2:3], 0x23200020
	v_lshl_add_u32 v215, v131, 2, 0
	v_lshlrev_b32_e32 v216, 4, v130
	s_mov_b32 s90, 0xff800000
	v_readfirstlane_b32 s8, v1
	s_ashr_i32 s9, s8, 31
	s_lshl_b64 s[8:9], s[8:9], 18
	s_add_u32 s10, s80, s8
	s_addc_u32 s11, s81, s9
	s_lshl_b64 s[12:13], s[0:1], 11
	s_add_u32 s0, s10, s12
	s_addc_u32 s1, s11, s13
	global_load_dwordx4 v[6:9], v132, s[0:1] offset:1024 nt
	global_load_dwordx4 v[2:5], v132, s[0:1] nt
	s_add_u32 s0, s78, s8
	s_addc_u32 s1, s79, s9
	s_add_u32 s8, s0, s12
	s_addc_u32 s9, s1, s13
	s_lshl_b64 s[14:15], s[4:5], 11
	s_add_u32 s12, s0, s14
	s_addc_u32 s13, s1, s15
	s_lshl_b64 s[18:19], s[16:17], 11
	s_add_u32 s16, s0, s18
	s_addc_u32 s17, s1, s19
	s_lshl_b64 s[22:23], s[20:21], 11
	s_add_u32 s20, s0, s22
	s_addc_u32 s21, s1, s23
	s_lshl_b64 s[28:29], s[24:25], 11
	s_add_u32 s24, s0, s28
	global_load_dwordx4 v[26:29], v132, s[8:9] offset:1024 nt
	global_load_dwordx4 v[30:33], v132, s[8:9] nt
	s_addc_u32 s25, s1, s29
	s_lshl_b64 s[8:9], s[30:31], 11
	s_add_u32 s30, s0, s8
	s_addc_u32 s31, s1, s9
	s_lshl_b64 s[36:37], s[36:37], 11
	s_add_u32 s84, s0, s36
	s_addc_u32 s85, s1, s37
	s_lshl_b64 s[60:61], s[60:61], 11
	global_load_dwordx4 v[62:65], v132, s[84:85] nt
	global_load_dwordx4 v[58:61], v132, s[84:85] offset:1024 nt
	s_add_u32 s84, s0, s60
	s_addc_u32 s85, s1, s61
	s_add_u32 s60, s10, s60
	s_addc_u32 s61, s11, s61
	s_add_u32 s36, s10, s36
	s_addc_u32 s37, s11, s37
	global_load_dwordx4 v[54:57], v132, s[84:85] nt
	global_load_dwordx4 v[50:53], v132, s[84:85] offset:1024 nt
	global_load_dwordx4 v[22:25], v132, s[60:61] offset:1024 nt
	global_load_dwordx4 v[14:17], v132, s[60:61] nt
	global_load_dwordx4 v[18:21], v132, s[36:37] offset:1024 nt
	global_load_dwordx4 v[10:13], v132, s[36:37] nt
	s_add_u32 s36, s10, s8
	s_addc_u32 s37, s11, s9
	s_mov_b64 s[8:9], 0x1000000
	v_lshl_add_u64 v[34:35], v[34:35], 0, s[8:9]
	global_load_dwordx2 v[34:35], v[34:35], off offset:512
	s_nop 0
	global_load_dwordx2 v[36:37], v[36:37], off
	s_nop 0
	global_load_dwordx4 v[66:69], v132, s[36:37] offset:1024 nt
	global_load_dwordx4 v[70:73], v132, s[36:37] nt
	s_add_u32 s28, s10, s28
	s_addc_u32 s29, s11, s29
	s_add_u32 s22, s10, s22
	s_addc_u32 s23, s11, s23
	s_add_u32 s18, s10, s18
	s_addc_u32 s19, s11, s19
	s_add_u32 s14, s10, s14
	s_addc_u32 s15, s11, s15
	global_load_dwordx4 v[118:121], v132, s[30:31] nt
	global_load_dwordx4 v[114:117], v132, s[30:31] offset:1024 nt
	s_lshl_b32 s5, s58, 12
	s_add_i32 s5, s5, 0
	s_mulk_i32 s58, 0xf020
	v_add_u32_e32 v1, s5, v132
	s_add_i32 s5, s5, s58
	v_add_u32_e32 v214, s5, v134
	v_lshlrev_b32_e32 v134, 2, v137
	v_and_b32_e32 v134, 4, v134
	s_movk_i32 s37, 0x88
	v_add3_u32 v134, v138, v134, v135
	v_mul_lo_u32 v134, v134, s37
	v_ashrrev_i32_e32 v135, 31, v134
	v_lshl_add_u64 v[134:135], v[134:135], 2, v[186:187]
	v_lshl_add_u64 v[190:191], v[134:135], 0, s[2:3]
	v_readlane_b32 s2, v245, 51
	s_lshl_b32 s2, s2, 1
	v_readlane_b32 s3, v245, 52
	s_andn2_b32 s2, s2, 63
	s_lshl_b32 s3, s3, 1
	v_lshlrev_b32_e32 v134, 1, v137
	s_or_b32 s2, s2, s3
	v_and_or_b32 v134, v134, 2, v139
	s_add_i32 s86, s2, 0x100
	v_lshl_add_u32 v134, v134, 1, v138
	s_lshl_b32 s85, s33, 1
	s_movk_i32 s36, 0x100
	v_mul_lo_u32 v140, v131, s37
	s_ashr_i32 s87, s86, 31
	s_mul_i32 s3, s86, 0x1100
	v_lshl_add_u32 v186, v134, 2, 0
	v_and_b32_e32 v134, -8, v131
	s_mul_hi_i32 s2, s86, 0x1100
	v_lshl_add_u32 v137, v137, 10, 0
	v_mov_b32_e32 v135, v187
	s_mov_b32 s84, 2
	v_add_u32_e32 v217, v137, v132
	v_readfirstlane_b32 s26, v133
	s_waitcnt vmcnt(5)
	v_lshlrev_b32_e32 v219, 16, v34
	v_and_b32_e32 v220, 0xffff0000, v34
	v_lshlrev_b32_e32 v198, 16, v35
	v_and_b32_e32 v199, 0xffff0000, v35
	s_waitcnt vmcnt(4)
	v_lshlrev_b32_e32 v221, 16, v36
	v_and_b32_e32 v222, 0xffff0000, v36
	v_lshlrev_b32_e32 v200, 16, v37
	v_and_b32_e32 v201, 0xffff0000, v37
	global_load_dwordx4 v[74:77], v132, s[28:29] offset:1024 nt
	global_load_dwordx4 v[34:37], v132, s[28:29] nt
	global_load_dwordx4 v[94:97], v132, s[24:25] nt
	global_load_dwordx4 v[90:93], v132, s[24:25] offset:1024 nt
	global_load_dwordx4 v[78:81], v132, s[22:23] offset:1024 nt
	global_load_dwordx4 v[46:49], v132, s[22:23] nt
	global_load_dwordx4 v[102:105], v132, s[20:21] nt
	global_load_dwordx4 v[98:101], v132, s[20:21] offset:1024 nt
	global_load_dwordx4 v[82:85], v132, s[18:19] offset:1024 nt
	global_load_dwordx4 v[42:45], v132, s[18:19] nt
	global_load_dwordx4 v[110:113], v132, s[16:17] nt
	global_load_dwordx4 v[106:109], v132, s[16:17] offset:1024 nt
	global_load_dwordx4 v[86:89], v132, s[14:15] offset:1024 nt
	global_load_dwordx4 v[38:41], v132, s[14:15] nt
	global_load_dwordx4 v[126:129], v132, s[12:13] nt
	global_load_dwordx4 v[122:125], v132, s[12:13] offset:1024 nt
	s_or_b32 s12, s4, 8
	s_ashr_i32 s13, s12, 31
	s_lshl_b64 s[14:15], s[12:13], 9
	s_or_b32 s12, s4, 9
	s_ashr_i32 s13, s12, 31
	s_lshl_b64 s[16:17], s[12:13], 9
	s_or_b32 s12, s4, 10
	s_ashr_i32 s13, s12, 31
	s_lshl_b64 s[18:19], s[12:13], 9
	s_or_b32 s12, s4, 11
	s_ashr_i32 s13, s12, 31
	s_lshl_b64 s[20:21], s[12:13], 9
	s_or_b32 s12, s4, 13
	s_ashr_i32 s13, s12, 31
	s_or_b32 s22, s4, 12
	s_lshl_b64 s[24:25], s[12:13], 9
	s_or_b32 s12, s4, 14
	s_or_b32 s4, s4, 15
	s_ashr_i32 s23, s22, 31
	s_ashr_i32 s13, s12, 31
	s_ashr_i32 s5, s4, 31
	s_lshl_b64 s[22:23], s[22:23], 9
	s_lshl_b64 s[28:29], s[12:13], 9
	s_lshl_b64 s[30:31], s[4:5], 9
	s_add_u32 s12, s96, s3
	v_cmp_eq_u32_e64 s[4:5], s36, v134
	v_add_u32_e32 v134, 0xffff7800, v140
	s_addc_u32 s13, s97, s2
	v_cmp_gt_i32_e64 s[2:3], s36, v131
	s_sub_i32 s88, s56, s57
	v_lshlrev_b64 v[192:193], 2, v[134:135]
	s_lshl_b64 s[14:15], s[14:15], 2
	s_lshl_b64 s[16:17], s[16:17], 2
	s_lshl_b64 s[18:19], s[18:19], 2
	s_lshl_b64 s[20:21], s[20:21], 2
	s_lshl_b64 s[22:23], s[22:23], 2
	s_lshl_b64 s[24:25], s[24:25], 2
	s_lshl_b64 s[28:29], s[28:29], 2
	s_lshl_b64 s[30:31], s[30:31], 2
	s_lshl_b64 s[36:37], s[6:7], 2
	s_lshl_b64 s[38:39], s[38:39], 2
	s_lshl_b64 s[40:41], s[40:41], 2
	s_lshl_b64 s[42:43], s[42:43], 2
	s_lshl_b64 s[44:45], s[44:45], 2
	s_lshl_b64 s[46:47], s[46:47], 2
	s_lshl_b64 s[48:49], s[48:49], 2
	s_lshl_b64 s[50:51], s[50:51], 2
	s_ashr_i32 s89, s33, 31
	v_cmp_eq_u32_e64 s[6:7], 0, v136
	s_branch .LBB0_628

.LBB0_882:
	v_readlane_b32 s0, v245, 2
	v_readlane_b32 s3, v245, 5
	s_bitcmp0_b32 s3, 5
	v_readlane_b32 s85, v245, 50
	v_readlane_b32 s92, v245, 43
	v_readlane_b32 s1, v245, 3
	v_readlane_b32 s2, v245, 4
	s_cbranch_scc1 .LBB0_893
	s_and_b32 s33, s95, -2
	s_ashr_i32 s1, s95, 31
	s_add_i32 s0, s33, s1
	s_xor_b32 s2, s0, s1
	v_cvt_f32_u32_e32 v1, s2
	v_readlane_b32 s0, v245, 54
	s_lshl_b32 s0, s0, 1
	s_sub_i32 s3, s33, s0
	v_rcp_iflag_f32_e32 v1, v1
	s_addk_i32 s3, 0x6fe
	s_ashr_i32 s4, s3, 31
	s_sub_i32 s5, 0, s2
	v_mul_f32_e32 v1, 0x4f7ffffe, v1
	v_cvt_u32_f32_e32 v1, v1
	s_xor_b32 s20, s4, s1
	s_abs_i32 s3, s3
	v_mov_b32_e32 v131, v0
	v_readfirstlane_b32 s1, v1
	s_mul_i32 s5, s5, s1
	s_mul_hi_u32 s4, s1, s5
	s_add_i32 s1, s1, s4
	s_mul_hi_u32 s1, s3, s1
	s_mul_i32 s4, s1, s2
	s_sub_i32 s3, s3, s4
	s_add_i32 s5, s1, 1
	s_sub_i32 s4, s3, s2
	s_cmp_ge_u32 s3, s2
	s_cselect_b32 s1, s5, s1
	s_cselect_b32 s3, s4, s3
	s_add_i32 s4, s1, 1
	s_cmp_ge_u32 s3, s2
	s_cselect_b32 s1, s4, s1
	s_xor_b32 s21, s1, s20
	s_sub_i32 s77, s21, s20
	s_cmp_lt_i32 s77, 1
	v_readfirstlane_b32 s1, v131
	s_cbranch_scc1 .LBB0_893
	s_add_u32 s10, s96, 0xce00000
	v_readlane_b32 s36, v245, 9
	s_addc_u32 s11, s97, 0
	s_ashr_i32 s16, s1, 6
	s_ashr_i32 s1, s0, 31
	v_readlane_b32 s38, v245, 11
	v_readlane_b32 s39, v245, 12
	s_add_i32 s4, s0, 0x101
	s_lshl_b64 s[0:1], s[0:1], 2
	s_mov_b64 s[14:15], s[38:39]
	s_add_u32 s0, s14, s0
	s_addc_u32 s1, s15, s1
	v_mov_b32_e32 v187, 0
	global_load_dword v1, v187, s[0:1] offset:1028
	s_cmp_lg_u32 s77, 1
	s_cselect_b32 s2, s33, 0
	s_ashr_i32 s3, s2, 31
	s_lshl_b64 s[2:3], s[2:3], 2
	s_add_u32 s0, s0, s2
	s_addc_u32 s1, s1, s3
	s_lshl_b32 s12, s16, 4
	s_ashr_i32 s2, s4, 4
	global_load_dword v22, v187, s[0:1] offset:1028
	s_or_b32 s18, s12, 1
	s_or_b32 s22, s12, 2
	s_or_b32 s24, s12, 3
	s_or_b32 s14, s12, 4
	s_or_b32 s6, s12, 5
	s_or_b32 s0, s12, 6
	s_or_b32 s4, s12, 7
	v_readlane_b32 s37, v245, 10
	v_readlane_b32 s40, v245, 13
	v_readlane_b32 s41, v245, 14
	v_readlane_b32 s42, v245, 15
	v_readlane_b32 s43, v245, 16
	v_readlane_b32 s44, v245, 17
	v_readlane_b32 s45, v245, 18
	v_readlane_b32 s46, v245, 19
	v_readlane_b32 s47, v245, 20
	v_readlane_b32 s48, v245, 21
	v_readlane_b32 s49, v245, 22
	s_ashr_i32 s13, s12, 31
	s_ashr_i32 s3, s2, 31
	s_ashr_i32 s19, s18, 31
	s_ashr_i32 s23, s22, 31
	s_ashr_i32 s25, s24, 31
	s_ashr_i32 s15, s14, 31
	s_ashr_i32 s7, s6, 31
	s_ashr_i32 s1, s0, 31
	s_ashr_i32 s5, s4, 31
	s_lshl_b64 s[30:31], s[12:13], 9
	s_lshl_b64 s[2:3], s[2:3], 10
	s_lshl_b64 s[36:37], s[18:19], 9
	s_lshl_b64 s[38:39], s[22:23], 9
	s_lshl_b64 s[40:41], s[24:25], 9
	s_lshl_b64 s[42:43], s[14:15], 9
	s_lshl_b64 s[44:45], s[6:7], 9
	s_lshl_b64 s[46:47], s[0:1], 9
	s_lshl_b64 s[48:49], s[4:5], 9
	v_and_b32_e32 v130, 63, v131
	s_add_u32 s2, s10, s2
	v_lshlrev_b32_e32 v186, 3, v130
	s_addc_u32 s3, s11, s3
	s_waitcnt vmcnt(0)
	v_lshl_add_u64 v[10:11], s[2:3], 0, v[186:187]
	v_readlane_b32 s50, v245, 23
	v_readlane_b32 s51, v245, 24
	v_lshlrev_b32_e32 v136, 4, v130
	s_mov_b32 s82, 0x1000000
	v_add_co_u32_e32 v12, vcc, s82, v10
	v_bfe_u32 v132, v131, 2, 4
	s_nop 0
	v_addc_co_u32_e32 v13, vcc, 0, v11, vcc
	v_ashrrev_i32_e32 v135, 6, v131
	v_bfe_u32 v138, v131, 5, 1
	v_ashrrev_i32_e32 v137, 7, v131
	v_and_b32_e32 v134, 31, v131
	v_lshl_add_u32 v216, v131, 2, 0
	v_lshl_add_u64 v[188:189], s[10:11], 0, v[186:187]
	v_lshlrev_b32_e32 v186, 4, v134
	v_lshl_add_u32 v139, v135, 10, 0
	s_mov_b64 s[10:11], 0x23201120
	v_mov_b32_e32 v133, v187
	s_mov_b32 s87, s85
	s_mov_b32 s68, 2
	s_mov_b32 s76, 0xff800000
	v_add_u32_e32 v217, v139, v136
	v_readfirstlane_b32 s2, v1
	s_ashr_i32 s3, s2, 31
	s_lshl_b64 s[2:3], s[2:3], 18
	s_add_u32 s50, s80, s2
	s_addc_u32 s51, s81, s3
	s_lshl_b64 s[4:5], s[4:5], 11
	s_add_u32 s8, s50, s4
	s_addc_u32 s9, s51, s5
	global_load_dwordx4 v[6:9], v136, s[8:9] offset:1024 nt
	global_load_dwordx4 v[2:5], v136, s[8:9] nt
	s_add_u32 s8, s78, s2
	s_addc_u32 s9, s79, s3
	s_add_u32 s28, s8, s4
	s_addc_u32 s29, s9, s5
	s_lshl_b64 s[4:5], s[12:13], 11
	s_add_u32 s2, s8, s4
	s_addc_u32 s3, s9, s5
	s_lshl_b64 s[18:19], s[18:19], 11
	global_load_dwordx4 v[66:69], v136, s[28:29] offset:1024 nt
	global_load_dwordx4 v[70:73], v136, s[28:29] nt
	s_add_u32 s28, s8, s18
	s_addc_u32 s29, s9, s19
	s_lshl_b64 s[22:23], s[22:23], 11
	s_add_u32 s56, s8, s22
	s_addc_u32 s57, s9, s23
	s_lshl_b64 s[24:25], s[24:25], 11
	s_add_u32 s58, s8, s24
	s_addc_u32 s59, s9, s25
	s_lshl_b64 s[14:15], s[14:15], 11
	s_add_u32 s72, s8, s14
	s_addc_u32 s73, s9, s15
	s_lshl_b64 s[6:7], s[6:7], 11
	s_add_u32 s74, s8, s6
	s_addc_u32 s75, s9, s7
	s_lshl_b64 s[0:1], s[0:1], 11
	s_add_u32 s52, s8, s0
	s_addc_u32 s53, s9, s1
	global_load_dwordx4 v[74:77], v136, s[52:53] nt
	global_load_dwordx4 v[78:81], v136, s[52:53] offset:1024 nt
	s_add_u32 s52, s50, s0
	s_addc_u32 s53, s51, s1
	s_mov_b64 s[0:1], 0x1000000
	v_lshl_add_u64 v[10:11], v[10:11], 0, s[0:1]
	global_load_dwordx2 v[14:15], v[10:11], off offset:512
	global_load_dwordx2 v[16:17], v[12:13], off
	s_add_u32 s6, s50, s6
	s_addc_u32 s7, s51, s7
	global_load_dwordx4 v[18:21], v136, s[52:53] offset:1024 nt
	global_load_dwordx4 v[10:13], v136, s[52:53] nt
	v_readfirstlane_b32 s26, v22
	s_movk_i32 s53, 0x88
	s_waitcnt vmcnt(3)
	v_lshlrev_b32_e32 v219, 16, v14
	v_and_b32_e32 v220, 0xffff0000, v14
	v_lshlrev_b32_e32 v198, 16, v15
	v_and_b32_e32 v199, 0xffff0000, v15
	s_waitcnt vmcnt(2)
	v_lshlrev_b32_e32 v221, 16, v16
	v_and_b32_e32 v222, 0xffff0000, v16
	v_lshlrev_b32_e32 v200, 16, v17
	v_and_b32_e32 v201, 0xffff0000, v17
	global_load_dwordx4 v[22:25], v136, s[6:7] offset:1024 nt
	global_load_dwordx4 v[14:17], v136, s[6:7] nt
	global_load_dwordx4 v[102:105], v136, s[74:75] nt
	global_load_dwordx4 v[98:101], v136, s[74:75] offset:1024 nt
	s_add_u32 s6, s50, s14
	s_addc_u32 s7, s51, s15
	global_load_dwordx4 v[58:61], v136, s[6:7] offset:1024 nt
	global_load_dwordx4 v[62:65], v136, s[6:7] nt
	global_load_dwordx4 v[118:121], v136, s[72:73] nt
	global_load_dwordx4 v[114:117], v136, s[72:73] offset:1024 nt
	s_add_u32 s6, s50, s24
	s_addc_u32 s7, s51, s25
	global_load_dwordx4 v[42:45], v136, s[6:7] offset:1024 nt
	global_load_dwordx4 v[26:29], v136, s[6:7] nt
	global_load_dwordx4 v[86:89], v136, s[58:59] nt
	global_load_dwordx4 v[82:85], v136, s[58:59] offset:1024 nt
	s_add_u32 s6, s50, s22
	s_addc_u32 s7, s51, s23
	global_load_dwordx4 v[46:49], v136, s[6:7] offset:1024 nt
	global_load_dwordx4 v[38:41], v136, s[6:7] nt
	global_load_dwordx4 v[94:97], v136, s[56:57] nt
	global_load_dwordx4 v[90:93], v136, s[56:57] offset:1024 nt
	s_add_u32 s6, s50, s18
	s_addc_u32 s7, s51, s19
	s_add_u32 s4, s50, s4
	s_addc_u32 s5, s51, s5
	global_load_dwordx4 v[50:53], v136, s[6:7] offset:1024 nt
	global_load_dwordx4 v[34:37], v136, s[6:7] nt
	global_load_dwordx4 v[110:113], v136, s[28:29] nt
	global_load_dwordx4 v[106:109], v136, s[28:29] offset:1024 nt
	global_load_dwordx4 v[54:57], v136, s[4:5] offset:1024 nt
	global_load_dwordx4 v[30:33], v136, s[4:5] nt
	global_load_dwordx4 v[126:129], v136, s[2:3] nt
	global_load_dwordx4 v[122:125], v136, s[2:3] offset:1024 nt
	s_lshl_b32 s2, s16, 12
	s_add_i32 s4, s2, 0
	s_mulk_i32 s16, 0xf020
	v_add_u32_e32 v1, s4, v136
	s_add_i32 s4, s4, s16
	v_add_u32_e32 v214, s4, v132
	v_lshlrev_b32_e32 v132, 1, v135
	v_and_or_b32 v132, v132, 2, v138
	v_lshl_add_u32 v132, v132, 1, v137
	s_movk_i32 s6, 0x100
	v_lshl_add_u32 v215, v132, 2, 0
	v_and_b32_e32 v132, -8, v131
	v_cmp_gt_i32_e64 s[4:5], s6, v131
	v_cmp_eq_u32_e64 s[6:7], s6, v132
	v_mul_lo_u32 v132, v131, s53
	v_lshlrev_b32_e32 v131, 2, v135
	v_cmp_eq_u32_e64 s[2:3], 0, v134
	v_and_b32_e32 v131, 4, v131
	v_lshlrev_b32_e32 v134, 1, v138
	v_add3_u32 v131, v137, v131, v134
	v_mul_lo_u32 v134, v131, s53
	v_ashrrev_i32_e32 v135, 31, v134
	v_lshl_add_u64 v[134:135], v[134:135], 2, v[186:187]
	v_lshl_add_u64 v[190:191], v[134:135], 0, s[10:11]
	v_readlane_b32 s10, v245, 51
	s_lshl_b32 s10, s10, 1
	v_readlane_b32 s11, v245, 52
	s_or_b32 s14, s12, 8
	s_or_b32 s22, s12, 12
	s_or_b32 s16, s12, 9
	s_or_b32 s18, s12, 10
	s_or_b32 s24, s12, 11
	s_or_b32 s28, s12, 13
	s_or_b32 s56, s12, 14
	s_or_b32 s12, s12, 15
	s_andn2_b32 s10, s10, 63
	s_lshl_b32 s11, s11, 1
	s_ashr_i32 s13, s12, 31
	s_or_b32 s10, s10, s11
	s_ashr_i32 s15, s14, 31
	s_ashr_i32 s17, s16, 31
	s_ashr_i32 s19, s18, 31
	s_ashr_i32 s25, s24, 31
	s_ashr_i32 s23, s22, 31
	s_ashr_i32 s29, s28, 31
	s_ashr_i32 s57, s56, 31
	s_lshl_b64 s[58:59], s[12:13], 9
	s_add_i32 s12, s10, 0x100
	s_lshl_b32 s69, s33, 1
	s_lshl_b64 s[14:15], s[14:15], 9
	s_lshl_b64 s[16:17], s[16:17], 9
	s_lshl_b64 s[18:19], s[18:19], 9
	s_lshl_b64 s[24:25], s[24:25], 9
	s_lshl_b64 s[22:23], s[22:23], 9
	s_lshl_b64 s[28:29], s[28:29], 9
	s_lshl_b64 s[56:57], s[56:57], 9
	s_ashr_i32 s72, s12, 31
	s_mul_i32 s10, s12, 0x1100
	v_add_u32_e32 v132, 0xffff7800, v132
	s_mul_hi_i32 s11, s12, 0x1100
	s_add_u32 s10, s96, s10
	s_addc_u32 s11, s97, s11
	s_ashr_i32 s73, s33, 31
	v_lshlrev_b64 v[192:193], 2, v[132:133]
	s_or_b32 s74, s12, 1
	s_sub_i32 s75, s20, s21
	s_lshl_b64 s[12:13], s[14:15], 2
	v_lshlrev_b32_e32 v186, 4, v130
	s_lshl_b64 s[14:15], s[16:17], 2
	s_lshl_b64 s[16:17], s[18:19], 2
	s_lshl_b64 s[18:19], s[24:25], 2
	s_lshl_b64 s[20:21], s[22:23], 2
	s_lshl_b64 s[22:23], s[28:29], 2
	s_lshl_b64 s[24:25], s[56:57], 2
	s_lshl_b64 s[28:29], s[58:59], 2
	s_lshl_b64 s[30:31], s[30:31], 2
	s_lshl_b64 s[36:37], s[36:37], 2
	s_lshl_b64 s[38:39], s[38:39], 2
	s_lshl_b64 s[40:41], s[40:41], 2
	s_lshl_b64 s[42:43], s[42:43], 2
	s_lshl_b64 s[44:45], s[44:45], 2
	s_lshl_b64 s[46:47], s[46:47], 2
	s_lshl_b64 s[48:49], s[48:49], 2
	s_branch .LBB0_886
